# K_FFN epilogue re-initialises each accumulator row block as soon as it is consumed (matrix pipe, idle during the epilogue); unit transition skips the re-init for those units
# speedup vs baseline: 1.0128x; 1.0006x over previous
; template <bool F8 = false, class Sched, class Epi>
; __device__ __forceinline__ void gemm_phase(LAS unsigned char* lds, const Sched& S, const Epi& E) {
;     ...
;         { const bool keep = Epi::keeps_acc(cur.kind);
; #pragma unroll
;         for (int a = 0; a < 2; ++a)
; #pragma unroll
;             for (int b = 0; b < 2; ++b)
; #pragma unroll
;                 for (int m = 0; m < 4; ++m)
; #pragma unroll
;                     for (int n = 0; n < 2; ++n)
; #pragma unroll
;                         for (int e = 0; e < 4; ++e) acc[a][b][m][n][e] = keep ? acc[a][b][m][n][e] : 0.f;
;         }
.LBB0_224:
	s_and_b64 vcc, exec, s[6:7]
	s_cbranch_vccnz .Lacc_keep
	s_cmp_eq_u32 s70, 8
	s_cbranch_scc1 .Lacc_keep
	v_mov_b64_e32 v[0:1], 0
	v_mov_b64_e32 v[2:3], 0
	v_mov_b64_e32 v[4:5], 0
	v_mov_b64_e32 v[6:7], 0
	v_mov_b64_e32 v[8:9], 0
	v_mov_b64_e32 v[10:11], 0
	v_mov_b64_e32 v[12:13], 0
	v_mov_b64_e32 v[14:15], 0
	v_mov_b64_e32 v[16:17], 0
	v_mov_b64_e32 v[18:19], 0
	v_mov_b64_e32 v[20:21], 0
	v_mov_b64_e32 v[22:23], 0
	v_mov_b64_e32 v[24:25], 0
	v_mov_b64_e32 v[26:27], 0
	v_mov_b64_e32 v[28:29], 0
	v_mov_b64_e32 v[30:31], 0
	v_mov_b64_e32 v[36:37], 0
	v_mov_b64_e32 v[38:39], 0
	v_mov_b64_e32 v[40:41], 0
	v_mov_b64_e32 v[42:43], 0
	v_mov_b64_e32 v[44:45], 0
	v_mov_b64_e32 v[46:47], 0
	v_mov_b64_e32 v[48:49], 0
	v_mov_b64_e32 v[50:51], 0
	v_mov_b64_e32 v[52:53], 0
	v_mov_b64_e32 v[54:55], 0
	v_mov_b64_e32 v[56:57], 0
	v_mov_b64_e32 v[58:59], 0
	v_mov_b64_e32 v[60:61], 0
	v_mov_b64_e32 v[62:63], 0
	v_mov_b64_e32 v[64:65], 0
	v_mov_b64_e32 v[66:67], 0
	v_mov_b64_e32 v[68:69], 0
	v_mov_b64_e32 v[70:71], 0
	v_mov_b64_e32 v[72:73], 0
	v_mov_b64_e32 v[74:75], 0
	v_mov_b64_e32 v[76:77], 0
	v_mov_b64_e32 v[78:79], 0
	v_mov_b64_e32 v[80:81], 0
	v_mov_b64_e32 v[82:83], 0
	v_mov_b64_e32 v[84:85], 0
	v_mov_b64_e32 v[86:87], 0
	v_mov_b64_e32 v[88:89], 0
	v_mov_b64_e32 v[90:91], 0
	v_mov_b64_e32 v[92:93], 0
	v_mov_b64_e32 v[94:95], 0
	v_mov_b64_e32 v[96:97], 0
	v_mov_b64_e32 v[98:99], 0
	v_mov_b64_e32 v[100:101], 0
	v_mov_b64_e32 v[102:103], 0
	v_mov_b64_e32 v[104:105], 0
	v_mov_b64_e32 v[106:107], 0
	v_mov_b64_e32 v[108:109], 0
	v_mov_b64_e32 v[110:111], 0
	v_mov_b64_e32 v[112:113], 0
	v_mov_b64_e32 v[114:115], 0
	v_mov_b64_e32 v[116:117], 0
	v_mov_b64_e32 v[118:119], 0
	v_mov_b64_e32 v[120:121], 0
	v_mov_b64_e32 v[122:123], 0
	v_mov_b64_e32 v[124:125], 0
	v_mov_b64_e32 v[126:127], 0
	v_mov_b64_e32 v[128:129], 0
	v_mov_b64_e32 v[130:131], 0

;     __device__ __forceinline__ void operator()(const f32x4 (&acc)[2][2][4][2], const GUnit& u, int wr, int wc, int fr, int fq, LAS unsigned char* lds) const {
;     ...
;                     for (int j = 0; j < 4; ++j) { const int g = (int)gp[m][j];
;                         const int oldu = m > 0 ? shl_((int)gp[m > 0 ? m - 1 : 0][j], lane15) : (int)eup[j];
;                         const int ups = __builtin_amdgcn_update_dpp(0, g, 0x111, 0xf, 0xf, true);
;                         const int oldd = m < 3 ? shl_((int)gp[m < 3 ? m + 1 : 3][j], lane0r) : (int)edp[j];
;                         const int dns = __builtin_amdgcn_update_dpp(0, g, 0x101, 0xf, 0xf, true);
;                         UP[j] = (unsigned)(frL == 0 ? oldu : ups); DN[j] = (unsigned)(frL == 15 ? oldd : dns); GG[j] = (unsigned)g; }
;                     const f16x8 uph = __builtin_bit_cast(f16x8, UP), dnh = __builtin_bit_cast(f16x8, DN), ggh = __builtin_bit_cast(f16x8, GG);
;                     f16x2 yv[4];
;                     yv[0] = __builtin_shufflevector(uph, uph, 0, 1) * w0p[0] + __builtin_shufflevector(ggh, ggh, 0, 1) * w1p[0] + __builtin_shufflevector(dnh, dnh, 0, 1) * w2p[0] + bbp[0];
;                     yv[1] = __builtin_shufflevector(uph, uph, 2, 3) * w0p[1] + __builtin_shufflevector(ggh, ggh, 2, 3) * w1p[1] + __builtin_shufflevector(dnh, dnh, 2, 3) * w2p[1] + bbp[1];
;                     yv[2] = __builtin_shufflevector(uph, uph, 4, 5) * w0p[2] + __builtin_shufflevector(ggh, ggh, 4, 5) * w1p[2] + __builtin_shufflevector(dnh, dnh, 4, 5) * w2p[2] + bbp[2];
;                     yv[3] = __builtin_shufflevector(uph, uph, 6, 7) * w0p[3] + __builtin_shufflevector(ggh, ggh, 6, 7) * w1p[3] + __builtin_shufflevector(dnh, dnh, 6, 7) * w2p[3] + bbp[3];
;                     u32x4 o;
; #pragma unroll
;                     for (int n = 0; n < 2; ++n)
; #pragma unroll
;                         for (int q = 0; q < 2; ++q) { const int j = 2 * n + q;
;                             if (m == 0 && c == 0 && frL == 0 && pmod != 0) { const size_t off = (size_t)(u.pm * 2 + 0) * DFF + fb + 4 * n + 2 * q; *(f32x2*)(GB + off) = (f32x2){acc[ai][1][0][n][2 * q], acc[ai][1][0][n][2 * q + 1]}; *(f32x2*)(YP + off) = (f32x2){(float)yv[j][0], (float)yv[j][1]}; *(f32x2*)(VB + off) = (f32x2){acc[ai][0][0][n][2 * q], acc[ai][0][0][n][2 * q + 1]}; }
.Lffn_side_top_skip:
	v_and_b32_e32 v138, 0x7fff7fff, v136
	v_and_b32_e32 v178, 0x7fff7fff, v176
	v_pk_fma_f16 v139, v138, s45, 1.0 op_sel_hi:[1,0,0]
	v_pk_fma_f16 v179, v178, s45, 1.0 op_sel_hi:[1,0,0]
	v_rcp_f16_e32 v183, v139
	v_rcp_f16_e32 v189, v179
	v_rcp_f16_sdwa v183, v139 dst_sel:WORD_1 dst_unused:UNUSED_PRESERVE src0_sel:WORD_1
	v_rcp_f16_sdwa v189, v179 dst_sel:WORD_1 dst_unused:UNUSED_PRESERVE src0_sel:WORD_1
	v_pk_fma_f16 v139, v183, s55, v228 op_sel_hi:[1,0,0]
	v_pk_fma_f16 v179, v189, s55, v228 op_sel_hi:[1,0,0]
	v_pk_fma_f16 v139, v183, v139, s65 op_sel_hi:[1,1,0]
	v_pk_fma_f16 v179, v189, v179, s65 op_sel_hi:[1,1,0]
	v_pk_fma_f16 v139, v183, v139, s68 op_sel_hi:[1,1,0]
	v_pk_fma_f16 v179, v189, v179, s68 op_sel_hi:[1,1,0]
	v_pk_fma_f16 v139, v183, v139, s69 op_sel_hi:[1,1,0]
	v_pk_fma_f16 v179, v189, v179, s69 op_sel_hi:[1,1,0]
	v_pk_mul_f16 v139, v183, v139
	v_pk_mul_f16 v179, v189, v179
	v_pk_mul_f16 v183, v136, v136
	v_pk_mul_f16 v189, v176, v176
	v_pk_mul_f16 v183, v183, s72 op_sel_hi:[1,0]
	v_pk_mul_f16 v189, v189, s72 op_sel_hi:[1,0]
	v_exp_f16_e32 v153, v183
	v_exp_f16_e32 v155, v189
	v_exp_f16_sdwa v153, v183 dst_sel:WORD_1 dst_unused:UNUSED_PRESERVE src0_sel:WORD_1
	v_exp_f16_sdwa v155, v189 dst_sel:WORD_1 dst_unused:UNUSED_PRESERVE src0_sel:WORD_1
	v_pk_mul_f16 v139, v153, v139
	v_pk_mul_f16 v179, v155, v179
	v_pk_max_f16 v136, v136, 0
	v_pk_max_f16 v176, v176, 0
	v_pk_fma_f16 v136, v138, v139, v136 neg_lo:[1,0,0] neg_hi:[1,0,0]
	v_pk_fma_f16 v176, v178, v179, v176 neg_lo:[1,0,0] neg_hi:[1,0,0]
	v_cvt_pk_f16_f32 v183, v128, v129
	v_cvt_pk_f16_f32 v189, v124, v125
	v_pk_mul_f16 v152, v183, v136
	v_pk_mul_f16 v154, v189, v176
	v_add_u32_e32 v152, 0x40004, v152
	v_add_u32_e32 v154, 0x40004, v154
	v_and_b32_e32 v152, 0xfff8fff8, v152
	v_and_b32_e32 v154, 0xfff8fff8, v154
	v_and_b32_e32 v136, 0x7fff7fff, v137
	v_and_b32_e32 v176, 0x7fff7fff, v177
	v_pk_fma_f16 v138, v136, s45, 1.0 op_sel_hi:[1,0,0]
	v_pk_fma_f16 v178, v176, s45, 1.0 op_sel_hi:[1,0,0]
	v_rcp_f16_e32 v139, v138
	v_rcp_f16_e32 v179, v178
	v_rcp_f16_sdwa v139, v138 dst_sel:WORD_1 dst_unused:UNUSED_PRESERVE src0_sel:WORD_1
	v_rcp_f16_sdwa v179, v178 dst_sel:WORD_1 dst_unused:UNUSED_PRESERVE src0_sel:WORD_1
	v_pk_fma_f16 v138, v139, s55, v228 op_sel_hi:[1,0,0]
	v_pk_fma_f16 v178, v179, s55, v228 op_sel_hi:[1,0,0]
	v_pk_fma_f16 v138, v139, v138, s65 op_sel_hi:[1,1,0]
	v_pk_fma_f16 v178, v179, v178, s65 op_sel_hi:[1,1,0]
	v_pk_fma_f16 v138, v139, v138, s68 op_sel_hi:[1,1,0]
	v_pk_fma_f16 v178, v179, v178, s68 op_sel_hi:[1,1,0]
	v_pk_fma_f16 v138, v139, v138, s69 op_sel_hi:[1,1,0]
	v_pk_fma_f16 v178, v179, v178, s69 op_sel_hi:[1,1,0]
	v_pk_mul_f16 v138, v139, v138
	v_pk_mul_f16 v178, v179, v178
	v_pk_mul_f16 v139, v137, v137
	v_pk_mul_f16 v179, v177, v177
	v_pk_mul_f16 v139, v139, s72 op_sel_hi:[1,0]
	v_pk_mul_f16 v179, v179, s72 op_sel_hi:[1,0]
	v_exp_f16_e32 v183, v139
	v_exp_f16_e32 v189, v179
	v_exp_f16_sdwa v183, v139 dst_sel:WORD_1 dst_unused:UNUSED_PRESERVE src0_sel:WORD_1
	v_exp_f16_sdwa v189, v179 dst_sel:WORD_1 dst_unused:UNUSED_PRESERVE src0_sel:WORD_1
	v_pk_mul_f16 v138, v183, v138
	v_pk_mul_f16 v178, v189, v178
	v_pk_max_f16 v137, v137, 0
	v_pk_max_f16 v177, v177, 0
	v_pk_fma_f16 v137, v136, v138, v137 neg_lo:[1,0,0] neg_hi:[1,0,0]
	v_pk_fma_f16 v177, v176, v178, v177 neg_lo:[1,0,0] neg_hi:[1,0,0]
	v_cvt_pk_f16_f32 v139, v130, v131
	v_cvt_pk_f16_f32 v179, v126, v127
	v_pk_mul_f16 v153, v139, v137
	v_pk_mul_f16 v155, v179, v177
	v_add_u32_e32 v153, 0x40004, v153
	v_add_u32_e32 v155, 0x40004, v155
	v_and_b32_e32 v153, 0xfff8fff8, v153
	v_and_b32_e32 v155, 0xfff8fff8, v155
	v_mad_i64_i32 v[194:195], vcc, v32, s29, v[192:193]
	global_store_dwordx4 v[194:195], v[152:155], off
	v_mov_b64_e32 v[116:117], 0
	v_mov_b64_e32 v[118:119], 0
	v_mov_b64_e32 v[120:121], 0
	v_mov_b64_e32 v[122:123], 0
	v_mov_b64_e32 v[124:125], 0
	v_mov_b64_e32 v[126:127], 0
	v_mov_b64_e32 v[128:129], 0
	v_mov_b64_e32 v[130:131], 0
	v_cvt_pk_f16_f32 v148, v88, v89
	v_cvt_pk_f16_f32 v149, v90, v91
	v_cvt_pk_f16_f32 v150, v84, v85
	v_cvt_pk_f16_f32 v151, v86, v87
	v_mov_b32_dpp v136, v140 row_ror:1 row_mask:0xf bank_mask:0xf
	v_mov_b32_dpp v176, v141 row_ror:1 row_mask:0xf bank_mask:0xf
	v_mov_b32_dpp v136, v144 row_shr:1 row_mask:0xf bank_mask:0xf
	v_mov_b32_dpp v176, v145 row_shr:1 row_mask:0xf bank_mask:0xf
	v_mov_b32_dpp v137, v148 row_ror:15 row_mask:0xf bank_mask:0xf
	v_mov_b32_dpp v177, v149 row_ror:15 row_mask:0xf bank_mask:0xf
	v_mov_b32_dpp v137, v144 row_shl:1 row_mask:0xf bank_mask:0xf
	v_mov_b32_dpp v177, v145 row_shl:1 row_mask:0xf bank_mask:0xf
	v_pk_fma_f16 v136, v136, v164, v160
	v_pk_fma_f16 v176, v176, v165, v161
	v_pk_fma_f16 v136, v144, v168, v136
	v_pk_fma_f16 v176, v145, v169, v176
	v_pk_fma_f16 v136, v137, v156, v136
	v_pk_fma_f16 v176, v177, v157, v176
	v_and_b32_e32 v137, 0x7fff7fff, v136
	v_and_b32_e32 v177, 0x7fff7fff, v176
	v_pk_fma_f16 v138, v137, s45, 1.0 op_sel_hi:[1,0,0]
	v_pk_fma_f16 v178, v177, s45, 1.0 op_sel_hi:[1,0,0]
	v_rcp_f16_e32 v139, v138
	v_rcp_f16_e32 v179, v178
	v_rcp_f16_sdwa v139, v138 dst_sel:WORD_1 dst_unused:UNUSED_PRESERVE src0_sel:WORD_1
	v_rcp_f16_sdwa v179, v178 dst_sel:WORD_1 dst_unused:UNUSED_PRESERVE src0_sel:WORD_1
	v_pk_fma_f16 v138, v139, s55, v228 op_sel_hi:[1,0,0]
	v_pk_fma_f16 v178, v179, s55, v228 op_sel_hi:[1,0,0]
	v_pk_fma_f16 v138, v139, v138, s65 op_sel_hi:[1,1,0]
	v_pk_fma_f16 v178, v179, v178, s65 op_sel_hi:[1,1,0]
	v_pk_fma_f16 v138, v139, v138, s68 op_sel_hi:[1,1,0]
	v_pk_fma_f16 v178, v179, v178, s68 op_sel_hi:[1,1,0]
	v_pk_fma_f16 v138, v139, v138, s69 op_sel_hi:[1,1,0]
	v_pk_fma_f16 v178, v179, v178, s69 op_sel_hi:[1,1,0]
; __device__ __forceinline__ int shl_(int v, int src_lane) { return __builtin_amdgcn_ds_bpermute(src_lane << 2, v); }
;     __device__ __forceinline__ void operator()(const f32x4 (&acc)[2][2][4][2], const GUnit& u, int wr, int wc, int fr, int fq, LAS unsigned char* lds) const {
;     ...
;                 for (int m = 0; m < 4; ++m) {
;                     u32x4 UP, DN, GG;
; #pragma unroll
;                     for (int j = 0; j < 4; ++j) { const int g = (int)gp[m][j];
;                         const int oldu = m > 0 ? shl_((int)gp[m > 0 ? m - 1 : 0][j], lane15) : (int)eup[j];
;                         const int ups = __builtin_amdgcn_update_dpp(0, g, 0x111, 0xf, 0xf, true);
;                         const int oldd = m < 3 ? shl_((int)gp[m < 3 ? m + 1 : 3][j], lane0r) : (int)edp[j];
;                         const int dns = __builtin_amdgcn_update_dpp(0, g, 0x101, 0xf, 0xf, true);
;                         UP[j] = (unsigned)(frL == 0 ? oldu : ups); DN[j] = (unsigned)(frL == 15 ? oldd : dns); GG[j] = (unsigned)g; }
;                     const f16x8 uph = __builtin_bit_cast(f16x8, UP), dnh = __builtin_bit_cast(f16x8, DN), ggh = __builtin_bit_cast(f16x8, GG);
;                     f16x2 yv[4];
;                     yv[0] = __builtin_shufflevector(uph, uph, 0, 1) * w0p[0] + __builtin_shufflevector(ggh, ggh, 0, 1) * w1p[0] + __builtin_shufflevector(dnh, dnh, 0, 1) * w2p[0] + bbp[0];
;                     yv[1] = __builtin_shufflevector(uph, uph, 2, 3) * w0p[1] + __builtin_shufflevector(ggh, ggh, 2, 3) * w1p[1] + __builtin_shufflevector(dnh, dnh, 2, 3) * w2p[1] + bbp[1];
;                     yv[2] = __builtin_shufflevector(uph, uph, 4, 5) * w0p[2] + __builtin_shufflevector(ggh, ggh, 4, 5) * w1p[2] + __builtin_shufflevector(dnh, dnh, 4, 5) * w2p[2] + bbp[2];
;                     yv[3] = __builtin_shufflevector(uph, uph, 6, 7) * w0p[3] + __builtin_shufflevector(ggh, ggh, 6, 7) * w1p[3] + __builtin_shufflevector(dnh, dnh, 6, 7) * w2p[3] + bbp[3];
;                     u32x4 o;
; #pragma unroll
;                     for (int n = 0; n < 2; ++n)
; #pragma unroll
;                         for (int q = 0; q < 2; ++q) { const int j = 2 * n + q;
	v_pk_mul_f16 v138, v139, v138
	v_pk_mul_f16 v178, v179, v178
	v_pk_mul_f16 v139, v136, v136
	v_pk_mul_f16 v179, v176, v176
	v_pk_mul_f16 v139, v139, s72 op_sel_hi:[1,0]
	v_pk_mul_f16 v179, v179, s72 op_sel_hi:[1,0]
	v_exp_f16_e32 v183, v139
	v_exp_f16_e32 v189, v179
	v_exp_f16_sdwa v183, v139 dst_sel:WORD_1 dst_unused:UNUSED_PRESERVE src0_sel:WORD_1
	v_exp_f16_sdwa v189, v179 dst_sel:WORD_1 dst_unused:UNUSED_PRESERVE src0_sel:WORD_1
	v_pk_mul_f16 v138, v183, v138
	v_pk_mul_f16 v178, v189, v178
	v_pk_max_f16 v136, v136, 0
	v_pk_max_f16 v176, v176, 0
	v_pk_fma_f16 v136, v137, v138, v136 neg_lo:[1,0,0] neg_hi:[1,0,0]
	v_pk_fma_f16 v176, v177, v178, v176 neg_lo:[1,0,0] neg_hi:[1,0,0]
	v_cvt_pk_f16_f32 v139, v112, v113
	v_cvt_pk_f16_f32 v179, v114, v115
	v_pk_mul_f16 v152, v139, v136
	v_pk_mul_f16 v153, v179, v176
	v_add_u32_e32 v152, 0x40004, v152
	v_add_u32_e32 v153, 0x40004, v153
	v_and_b32_e32 v152, 0xfff8fff8, v152
	v_and_b32_e32 v153, 0xfff8fff8, v153
	v_mov_b32_dpp v136, v142 row_ror:1 row_mask:0xf bank_mask:0xf
	v_mov_b32_dpp v176, v143 row_ror:1 row_mask:0xf bank_mask:0xf
	v_mov_b32_dpp v136, v146 row_shr:1 row_mask:0xf bank_mask:0xf
	v_mov_b32_dpp v176, v147 row_shr:1 row_mask:0xf bank_mask:0xf
	v_mov_b32_dpp v137, v150 row_ror:15 row_mask:0xf bank_mask:0xf
	v_mov_b32_dpp v177, v151 row_ror:15 row_mask:0xf bank_mask:0xf
	v_mov_b32_dpp v137, v146 row_shl:1 row_mask:0xf bank_mask:0xf
	v_mov_b32_dpp v177, v147 row_shl:1 row_mask:0xf bank_mask:0xf
	v_pk_fma_f16 v136, v136, v166, v162
	v_pk_fma_f16 v176, v176, v167, v163
	v_pk_fma_f16 v136, v146, v170, v136
	v_pk_fma_f16 v176, v147, v171, v176
	v_pk_fma_f16 v136, v137, v158, v136
	v_pk_fma_f16 v176, v177, v159, v176
	v_and_b32_e32 v137, 0x7fff7fff, v136
	v_and_b32_e32 v177, 0x7fff7fff, v176
	v_pk_fma_f16 v138, v137, s45, 1.0 op_sel_hi:[1,0,0]
	v_pk_fma_f16 v178, v177, s45, 1.0 op_sel_hi:[1,0,0]
	v_rcp_f16_e32 v139, v138
	v_rcp_f16_e32 v179, v178
	v_rcp_f16_sdwa v139, v138 dst_sel:WORD_1 dst_unused:UNUSED_PRESERVE src0_sel:WORD_1
	v_rcp_f16_sdwa v179, v178 dst_sel:WORD_1 dst_unused:UNUSED_PRESERVE src0_sel:WORD_1
	v_pk_fma_f16 v138, v139, s55, v228 op_sel_hi:[1,0,0]
	v_pk_fma_f16 v178, v179, s55, v228 op_sel_hi:[1,0,0]
	v_pk_fma_f16 v138, v139, v138, s65 op_sel_hi:[1,1,0]
	v_pk_fma_f16 v178, v179, v178, s65 op_sel_hi:[1,1,0]
	v_pk_fma_f16 v138, v139, v138, s68 op_sel_hi:[1,1,0]
	v_pk_fma_f16 v178, v179, v178, s68 op_sel_hi:[1,1,0]
	v_pk_fma_f16 v138, v139, v138, s69 op_sel_hi:[1,1,0]
	v_pk_fma_f16 v178, v179, v178, s69 op_sel_hi:[1,1,0]
	v_pk_mul_f16 v138, v139, v138
	v_pk_mul_f16 v178, v179, v178
	v_pk_mul_f16 v139, v136, v136
	v_pk_mul_f16 v179, v176, v176
	v_pk_mul_f16 v139, v139, s72 op_sel_hi:[1,0]
	v_pk_mul_f16 v179, v179, s72 op_sel_hi:[1,0]
	v_exp_f16_e32 v183, v139
	v_exp_f16_e32 v189, v179
	v_exp_f16_sdwa v183, v139 dst_sel:WORD_1 dst_unused:UNUSED_PRESERVE src0_sel:WORD_1
	v_exp_f16_sdwa v189, v179 dst_sel:WORD_1 dst_unused:UNUSED_PRESERVE src0_sel:WORD_1
	v_pk_mul_f16 v138, v183, v138
	v_pk_mul_f16 v178, v189, v178
	v_pk_max_f16 v136, v136, 0
	v_pk_max_f16 v176, v176, 0
	v_pk_fma_f16 v136, v137, v138, v136 neg_lo:[1,0,0] neg_hi:[1,0,0]
	v_pk_fma_f16 v176, v177, v178, v176 neg_lo:[1,0,0] neg_hi:[1,0,0]
	v_cvt_pk_f16_f32 v139, v108, v109
	v_cvt_pk_f16_f32 v179, v110, v111
	v_pk_mul_f16 v154, v139, v136
	v_pk_mul_f16 v155, v179, v176
	v_add_u32_e32 v154, 0x40004, v154
	v_add_u32_e32 v155, 0x40004, v155
	v_and_b32_e32 v154, 0xfff8fff8, v154
	v_and_b32_e32 v155, 0xfff8fff8, v155
	v_add_u32_e32 v194, 16, v32
	v_mad_i64_i32 v[194:195], vcc, v194, s29, v[192:193]
	global_store_dwordx4 v[194:195], v[152:155], off
	v_mfma_f32_32x32x16_f16 v[100:115], v[128:131], v[128:131], 0
	v_cvt_pk_f16_f32 v140, v72, v73
	v_cvt_pk_f16_f32 v141, v74, v75
	v_cvt_pk_f16_f32 v142, v68, v69
	v_cvt_pk_f16_f32 v143, v70, v71
	v_mov_b32_dpp v136, v144 row_ror:1 row_mask:0xf bank_mask:0xf
	v_mov_b32_dpp v176, v145 row_ror:1 row_mask:0xf bank_mask:0xf
	v_mov_b32_dpp v136, v148 row_shr:1 row_mask:0xf bank_mask:0xf
	v_mov_b32_dpp v176, v149 row_shr:1 row_mask:0xf bank_mask:0xf
	v_mov_b32_dpp v137, v140 row_ror:15 row_mask:0xf bank_mask:0xf
	v_mov_b32_dpp v177, v141 row_ror:15 row_mask:0xf bank_mask:0xf
	v_mov_b32_dpp v137, v148 row_shl:1 row_mask:0xf bank_mask:0xf
	v_mov_b32_dpp v177, v149 row_shl:1 row_mask:0xf bank_mask:0xf
	v_pk_fma_f16 v136, v136, v164, v160
	v_pk_fma_f16 v176, v176, v165, v161
	v_pk_fma_f16 v136, v148, v168, v136
	v_pk_fma_f16 v176, v149, v169, v176
	v_pk_fma_f16 v136, v137, v156, v136
	v_pk_fma_f16 v176, v177, v157, v176
	v_and_b32_e32 v137, 0x7fff7fff, v136
	v_and_b32_e32 v177, 0x7fff7fff, v176
	v_pk_fma_f16 v138, v137, s45, 1.0 op_sel_hi:[1,0,0]
	v_pk_fma_f16 v178, v177, s45, 1.0 op_sel_hi:[1,0,0]
	v_rcp_f16_e32 v139, v138
	v_rcp_f16_e32 v179, v178
	v_rcp_f16_sdwa v139, v138 dst_sel:WORD_1 dst_unused:UNUSED_PRESERVE src0_sel:WORD_1
	v_rcp_f16_sdwa v179, v178 dst_sel:WORD_1 dst_unused:UNUSED_PRESERVE src0_sel:WORD_1
	v_pk_fma_f16 v138, v139, s55, v228 op_sel_hi:[1,0,0]
	v_pk_fma_f16 v178, v179, s55, v228 op_sel_hi:[1,0,0]
	v_pk_fma_f16 v138, v139, v138, s65 op_sel_hi:[1,1,0]
	v_pk_fma_f16 v178, v179, v178, s65 op_sel_hi:[1,1,0]
	v_pk_fma_f16 v138, v139, v138, s68 op_sel_hi:[1,1,0]
	v_pk_fma_f16 v178, v179, v178, s68 op_sel_hi:[1,1,0]
	v_pk_fma_f16 v138, v139, v138, s69 op_sel_hi:[1,1,0]
	v_pk_fma_f16 v178, v179, v178, s69 op_sel_hi:[1,1,0]
	v_pk_mul_f16 v138, v139, v138
	v_pk_mul_f16 v178, v179, v178
	v_pk_mul_f16 v139, v136, v136
	v_pk_mul_f16 v179, v176, v176
	v_pk_mul_f16 v139, v139, s72 op_sel_hi:[1,0]
	v_pk_mul_f16 v179, v179, s72 op_sel_hi:[1,0]
	v_exp_f16_e32 v183, v139
; __device__ __forceinline__ int shl_(int v, int src_lane) { return __builtin_amdgcn_ds_bpermute(src_lane << 2, v); }
;     __device__ __forceinline__ void operator()(const f32x4 (&acc)[2][2][4][2], const GUnit& u, int wr, int wc, int fr, int fq, LAS unsigned char* lds) const {
;     ...
;                 for (int m = 0; m < 4; ++m) {
;                     u32x4 UP, DN, GG;
; #pragma unroll
;                     for (int j = 0; j < 4; ++j) { const int g = (int)gp[m][j];
;                         const int oldu = m > 0 ? shl_((int)gp[m > 0 ? m - 1 : 0][j], lane15) : (int)eup[j];
;                         const int ups = __builtin_amdgcn_update_dpp(0, g, 0x111, 0xf, 0xf, true);
;                         const int oldd = m < 3 ? shl_((int)gp[m < 3 ? m + 1 : 3][j], lane0r) : (int)edp[j];
;                         const int dns = __builtin_amdgcn_update_dpp(0, g, 0x101, 0xf, 0xf, true);
;                         UP[j] = (unsigned)(frL == 0 ? oldu : ups); DN[j] = (unsigned)(frL == 15 ? oldd : dns); GG[j] = (unsigned)g; }
;                     const f16x8 uph = __builtin_bit_cast(f16x8, UP), dnh = __builtin_bit_cast(f16x8, DN), ggh = __builtin_bit_cast(f16x8, GG);
;                     f16x2 yv[4];
;                     yv[0] = __builtin_shufflevector(uph, uph, 0, 1) * w0p[0] + __builtin_shufflevector(ggh, ggh, 0, 1) * w1p[0] + __builtin_shufflevector(dnh, dnh, 0, 1) * w2p[0] + bbp[0];
;                     yv[1] = __builtin_shufflevector(uph, uph, 2, 3) * w0p[1] + __builtin_shufflevector(ggh, ggh, 2, 3) * w1p[1] + __builtin_shufflevector(dnh, dnh, 2, 3) * w2p[1] + bbp[1];
;                     yv[2] = __builtin_shufflevector(uph, uph, 4, 5) * w0p[2] + __builtin_shufflevector(ggh, ggh, 4, 5) * w1p[2] + __builtin_shufflevector(dnh, dnh, 4, 5) * w2p[2] + bbp[2];
;                     yv[3] = __builtin_shufflevector(uph, uph, 6, 7) * w0p[3] + __builtin_shufflevector(ggh, ggh, 6, 7) * w1p[3] + __builtin_shufflevector(dnh, dnh, 6, 7) * w2p[3] + bbp[3];
;                     u32x4 o;
; #pragma unroll
;                     for (int n = 0; n < 2; ++n)
; #pragma unroll
;                         for (int q = 0; q < 2; ++q) { const int j = 2 * n + q;
	v_exp_f16_e32 v189, v179
	v_exp_f16_sdwa v183, v139 dst_sel:WORD_1 dst_unused:UNUSED_PRESERVE src0_sel:WORD_1
	v_exp_f16_sdwa v189, v179 dst_sel:WORD_1 dst_unused:UNUSED_PRESERVE src0_sel:WORD_1
	v_pk_mul_f16 v138, v183, v138
	v_pk_mul_f16 v178, v189, v178
	v_pk_max_f16 v136, v136, 0
	v_pk_max_f16 v176, v176, 0
	v_pk_fma_f16 v136, v137, v138, v136 neg_lo:[1,0,0] neg_hi:[1,0,0]
	v_pk_fma_f16 v176, v177, v178, v176 neg_lo:[1,0,0] neg_hi:[1,0,0]
	v_cvt_pk_f16_f32 v139, v96, v97
	v_cvt_pk_f16_f32 v179, v98, v99
	v_pk_mul_f16 v152, v139, v136
	v_pk_mul_f16 v153, v179, v176
	v_add_u32_e32 v152, 0x40004, v152
	v_add_u32_e32 v153, 0x40004, v153
	v_and_b32_e32 v152, 0xfff8fff8, v152
	v_and_b32_e32 v153, 0xfff8fff8, v153
	v_mov_b32_dpp v136, v146 row_ror:1 row_mask:0xf bank_mask:0xf
	v_mov_b32_dpp v176, v147 row_ror:1 row_mask:0xf bank_mask:0xf
	v_mov_b32_dpp v136, v150 row_shr:1 row_mask:0xf bank_mask:0xf
	v_mov_b32_dpp v176, v151 row_shr:1 row_mask:0xf bank_mask:0xf
	v_mov_b32_dpp v137, v142 row_ror:15 row_mask:0xf bank_mask:0xf
	v_mov_b32_dpp v177, v143 row_ror:15 row_mask:0xf bank_mask:0xf
	v_mov_b32_dpp v137, v150 row_shl:1 row_mask:0xf bank_mask:0xf
	v_mov_b32_dpp v177, v151 row_shl:1 row_mask:0xf bank_mask:0xf
	v_pk_fma_f16 v136, v136, v166, v162
	v_pk_fma_f16 v176, v176, v167, v163
	v_pk_fma_f16 v136, v150, v170, v136
	v_pk_fma_f16 v176, v151, v171, v176
	v_pk_fma_f16 v136, v137, v158, v136
	v_pk_fma_f16 v176, v177, v159, v176
	v_and_b32_e32 v137, 0x7fff7fff, v136
	v_and_b32_e32 v177, 0x7fff7fff, v176
	v_pk_fma_f16 v138, v137, s45, 1.0 op_sel_hi:[1,0,0]
	v_pk_fma_f16 v178, v177, s45, 1.0 op_sel_hi:[1,0,0]
	v_rcp_f16_e32 v139, v138
	v_rcp_f16_e32 v179, v178
	v_rcp_f16_sdwa v139, v138 dst_sel:WORD_1 dst_unused:UNUSED_PRESERVE src0_sel:WORD_1
	v_rcp_f16_sdwa v179, v178 dst_sel:WORD_1 dst_unused:UNUSED_PRESERVE src0_sel:WORD_1
	v_pk_fma_f16 v138, v139, s55, v228 op_sel_hi:[1,0,0]
	v_pk_fma_f16 v178, v179, s55, v228 op_sel_hi:[1,0,0]
	v_pk_fma_f16 v138, v139, v138, s65 op_sel_hi:[1,1,0]
	v_pk_fma_f16 v178, v179, v178, s65 op_sel_hi:[1,1,0]
	v_pk_fma_f16 v138, v139, v138, s68 op_sel_hi:[1,1,0]
	v_pk_fma_f16 v178, v179, v178, s68 op_sel_hi:[1,1,0]
	v_pk_fma_f16 v138, v139, v138, s69 op_sel_hi:[1,1,0]
	v_pk_fma_f16 v178, v179, v178, s69 op_sel_hi:[1,1,0]
	v_pk_mul_f16 v138, v139, v138
	v_pk_mul_f16 v178, v179, v178
	v_pk_mul_f16 v139, v136, v136
	v_pk_mul_f16 v179, v176, v176
	v_pk_mul_f16 v139, v139, s72 op_sel_hi:[1,0]
	v_pk_mul_f16 v179, v179, s72 op_sel_hi:[1,0]
	v_exp_f16_e32 v183, v139
	v_exp_f16_e32 v189, v179
	v_exp_f16_sdwa v183, v139 dst_sel:WORD_1 dst_unused:UNUSED_PRESERVE src0_sel:WORD_1
	v_exp_f16_sdwa v189, v179 dst_sel:WORD_1 dst_unused:UNUSED_PRESERVE src0_sel:WORD_1
	v_pk_mul_f16 v138, v183, v138
	v_pk_mul_f16 v178, v189, v178
	v_pk_max_f16 v136, v136, 0
	v_pk_max_f16 v176, v176, 0
	v_pk_fma_f16 v136, v137, v138, v136 neg_lo:[1,0,0] neg_hi:[1,0,0]
	v_pk_fma_f16 v176, v177, v178, v176 neg_lo:[1,0,0] neg_hi:[1,0,0]
	v_cvt_pk_f16_f32 v139, v92, v93
	v_cvt_pk_f16_f32 v179, v94, v95
	v_pk_mul_f16 v154, v139, v136
	v_pk_mul_f16 v155, v179, v176
	v_add_u32_e32 v154, 0x40004, v154
	v_add_u32_e32 v155, 0x40004, v155
	v_and_b32_e32 v154, 0xfff8fff8, v154
	v_and_b32_e32 v155, 0xfff8fff8, v155
	v_add_u32_e32 v194, 32, v32
	v_mad_i64_i32 v[194:195], vcc, v194, s29, v[192:193]
	global_store_dwordx4 v[194:195], v[152:155], off
	v_mfma_f32_32x32x16_f16 v[84:99], v[128:131], v[128:131], 0
	v_mov_b32_dpp v136, v148 row_ror:1 row_mask:0xf bank_mask:0xf
	v_mov_b32_dpp v176, v149 row_ror:1 row_mask:0xf bank_mask:0xf
	v_mov_b32_dpp v136, v140 row_shr:1 row_mask:0xf bank_mask:0xf
	v_mov_b32_dpp v176, v141 row_shr:1 row_mask:0xf bank_mask:0xf
	v_mov_b32_dpp v132, v140 row_shl:1 row_mask:0xf bank_mask:0xf
	v_mov_b32_dpp v133, v141 row_shl:1 row_mask:0xf bank_mask:0xf
	v_pk_fma_f16 v136, v136, v164, v160
	v_pk_fma_f16 v176, v176, v165, v161
	v_pk_fma_f16 v136, v140, v168, v136
	v_pk_fma_f16 v176, v141, v169, v176
	v_pk_fma_f16 v136, v132, v156, v136
	v_pk_fma_f16 v176, v133, v157, v176
	v_and_b32_e32 v137, 0x7fff7fff, v136
	v_and_b32_e32 v177, 0x7fff7fff, v176
	v_pk_fma_f16 v138, v137, s45, 1.0 op_sel_hi:[1,0,0]
	v_pk_fma_f16 v178, v177, s45, 1.0 op_sel_hi:[1,0,0]
	v_rcp_f16_e32 v139, v138
	v_rcp_f16_e32 v179, v178
	v_rcp_f16_sdwa v139, v138 dst_sel:WORD_1 dst_unused:UNUSED_PRESERVE src0_sel:WORD_1
	v_rcp_f16_sdwa v179, v178 dst_sel:WORD_1 dst_unused:UNUSED_PRESERVE src0_sel:WORD_1
; __device__ __forceinline__ int shl_(int v, int src_lane) { return __builtin_amdgcn_ds_bpermute(src_lane << 2, v); }
;     __device__ __forceinline__ void operator()(const f32x4 (&acc)[2][2][4][2], const GUnit& u, int wr, int wc, int fr, int fq, LAS unsigned char* lds) const {
;     ...
;                 for (int m = 0; m < 4; ++m) {
;                     u32x4 UP, DN, GG;
; #pragma unroll
;                     for (int j = 0; j < 4; ++j) { const int g = (int)gp[m][j];
;                         const int oldu = m > 0 ? shl_((int)gp[m > 0 ? m - 1 : 0][j], lane15) : (int)eup[j];
;                         const int ups = __builtin_amdgcn_update_dpp(0, g, 0x111, 0xf, 0xf, true);
;                         const int oldd = m < 3 ? shl_((int)gp[m < 3 ? m + 1 : 3][j], lane0r) : (int)edp[j];
;                         const int dns = __builtin_amdgcn_update_dpp(0, g, 0x101, 0xf, 0xf, true);
;                         UP[j] = (unsigned)(frL == 0 ? oldu : ups); DN[j] = (unsigned)(frL == 15 ? oldd : dns); GG[j] = (unsigned)g; }
;                     const f16x8 uph = __builtin_bit_cast(f16x8, UP), dnh = __builtin_bit_cast(f16x8, DN), ggh = __builtin_bit_cast(f16x8, GG);
;                     f16x2 yv[4];
;                     yv[0] = __builtin_shufflevector(uph, uph, 0, 1) * w0p[0] + __builtin_shufflevector(ggh, ggh, 0, 1) * w1p[0] + __builtin_shufflevector(dnh, dnh, 0, 1) * w2p[0] + bbp[0];
;                     yv[1] = __builtin_shufflevector(uph, uph, 2, 3) * w0p[1] + __builtin_shufflevector(ggh, ggh, 2, 3) * w1p[1] + __builtin_shufflevector(dnh, dnh, 2, 3) * w2p[1] + bbp[1];
;                     yv[2] = __builtin_shufflevector(uph, uph, 4, 5) * w0p[2] + __builtin_shufflevector(ggh, ggh, 4, 5) * w1p[2] + __builtin_shufflevector(dnh, dnh, 4, 5) * w2p[2] + bbp[2];
;                     yv[3] = __builtin_shufflevector(uph, uph, 6, 7) * w0p[3] + __builtin_shufflevector(ggh, ggh, 6, 7) * w1p[3] + __builtin_shufflevector(dnh, dnh, 6, 7) * w2p[3] + bbp[3];
;                     u32x4 o;
; #pragma unroll
;                     for (int n = 0; n < 2; ++n)
; #pragma unroll
;                         for (int q = 0; q < 2; ++q) { const int j = 2 * n + q;
	v_pk_fma_f16 v138, v139, s55, v228 op_sel_hi:[1,0,0]
	v_pk_fma_f16 v178, v179, s55, v228 op_sel_hi:[1,0,0]
	v_pk_fma_f16 v138, v139, v138, s65 op_sel_hi:[1,1,0]
	v_pk_fma_f16 v178, v179, v178, s65 op_sel_hi:[1,1,0]
	v_pk_fma_f16 v138, v139, v138, s68 op_sel_hi:[1,1,0]
	v_pk_fma_f16 v178, v179, v178, s68 op_sel_hi:[1,1,0]
	v_pk_fma_f16 v138, v139, v138, s69 op_sel_hi:[1,1,0]
	v_pk_fma_f16 v178, v179, v178, s69 op_sel_hi:[1,1,0]
	v_pk_mul_f16 v138, v139, v138
	v_pk_mul_f16 v178, v179, v178
	v_pk_mul_f16 v139, v136, v136
	v_pk_mul_f16 v179, v176, v176
	v_pk_mul_f16 v139, v139, s72 op_sel_hi:[1,0]
	v_pk_mul_f16 v179, v179, s72 op_sel_hi:[1,0]
	v_exp_f16_e32 v183, v139
	v_exp_f16_e32 v189, v179
	v_exp_f16_sdwa v183, v139 dst_sel:WORD_1 dst_unused:UNUSED_PRESERVE src0_sel:WORD_1
	v_exp_f16_sdwa v189, v179 dst_sel:WORD_1 dst_unused:UNUSED_PRESERVE src0_sel:WORD_1
	v_pk_mul_f16 v138, v183, v138
	v_pk_mul_f16 v178, v189, v178
	v_pk_max_f16 v136, v136, 0
	v_pk_max_f16 v176, v176, 0
	v_pk_fma_f16 v136, v137, v138, v136 neg_lo:[1,0,0] neg_hi:[1,0,0]
	v_pk_fma_f16 v176, v177, v178, v176 neg_lo:[1,0,0] neg_hi:[1,0,0]
	v_cvt_pk_f16_f32 v139, v80, v81
	v_cvt_pk_f16_f32 v179, v82, v83
	v_pk_mul_f16 v152, v139, v136
	v_pk_mul_f16 v153, v179, v176
	v_add_u32_e32 v152, 0x40004, v152
	v_add_u32_e32 v153, 0x40004, v153
	v_and_b32_e32 v152, 0xfff8fff8, v152
	v_and_b32_e32 v153, 0xfff8fff8, v153
	v_mov_b32_dpp v136, v150 row_ror:1 row_mask:0xf bank_mask:0xf
	v_mov_b32_dpp v176, v151 row_ror:1 row_mask:0xf bank_mask:0xf
	v_mov_b32_dpp v136, v142 row_shr:1 row_mask:0xf bank_mask:0xf
	v_mov_b32_dpp v176, v143 row_shr:1 row_mask:0xf bank_mask:0xf
	v_mov_b32_dpp v134, v142 row_shl:1 row_mask:0xf bank_mask:0xf
	v_mov_b32_dpp v135, v143 row_shl:1 row_mask:0xf bank_mask:0xf
	v_pk_fma_f16 v136, v136, v166, v162
	v_pk_fma_f16 v176, v176, v167, v163
	v_pk_fma_f16 v136, v142, v170, v136
	v_pk_fma_f16 v176, v143, v171, v176
	v_pk_fma_f16 v136, v134, v158, v136
	v_pk_fma_f16 v176, v135, v159, v176
	v_and_b32_e32 v137, 0x7fff7fff, v136
	v_and_b32_e32 v177, 0x7fff7fff, v176
	v_pk_fma_f16 v138, v137, s45, 1.0 op_sel_hi:[1,0,0]
	v_pk_fma_f16 v178, v177, s45, 1.0 op_sel_hi:[1,0,0]
	v_rcp_f16_e32 v139, v138
	v_rcp_f16_e32 v179, v178
	v_rcp_f16_sdwa v139, v138 dst_sel:WORD_1 dst_unused:UNUSED_PRESERVE src0_sel:WORD_1
	v_rcp_f16_sdwa v179, v178 dst_sel:WORD_1 dst_unused:UNUSED_PRESERVE src0_sel:WORD_1
	v_pk_fma_f16 v138, v139, s55, v228 op_sel_hi:[1,0,0]
	v_pk_fma_f16 v178, v179, s55, v228 op_sel_hi:[1,0,0]
	v_pk_fma_f16 v138, v139, v138, s65 op_sel_hi:[1,1,0]
	v_pk_fma_f16 v178, v179, v178, s65 op_sel_hi:[1,1,0]
	v_pk_fma_f16 v138, v139, v138, s68 op_sel_hi:[1,1,0]
	v_pk_fma_f16 v178, v179, v178, s68 op_sel_hi:[1,1,0]
	v_pk_fma_f16 v138, v139, v138, s69 op_sel_hi:[1,1,0]
	v_pk_fma_f16 v178, v179, v178, s69 op_sel_hi:[1,1,0]
	v_pk_mul_f16 v138, v139, v138
	v_pk_mul_f16 v178, v179, v178
	v_pk_mul_f16 v139, v136, v136
	v_pk_mul_f16 v179, v176, v176
	v_pk_mul_f16 v139, v139, s72 op_sel_hi:[1,0]
	v_pk_mul_f16 v179, v179, s72 op_sel_hi:[1,0]
	v_exp_f16_e32 v183, v139
	v_exp_f16_e32 v189, v179
	v_exp_f16_sdwa v183, v139 dst_sel:WORD_1 dst_unused:UNUSED_PRESERVE src0_sel:WORD_1
	v_exp_f16_sdwa v189, v179 dst_sel:WORD_1 dst_unused:UNUSED_PRESERVE src0_sel:WORD_1
	v_pk_mul_f16 v138, v183, v138
	v_pk_mul_f16 v178, v189, v178
	v_pk_max_f16 v136, v136, 0
	v_pk_max_f16 v176, v176, 0
	v_pk_fma_f16 v136, v137, v138, v136 neg_lo:[1,0,0] neg_hi:[1,0,0]
	v_pk_fma_f16 v176, v177, v178, v176 neg_lo:[1,0,0] neg_hi:[1,0,0]
	v_cvt_pk_f16_f32 v139, v76, v77
	v_cvt_pk_f16_f32 v179, v78, v79
	v_pk_mul_f16 v154, v139, v136
	v_pk_mul_f16 v155, v179, v176
	v_add_u32_e32 v154, 0x40004, v154
	v_add_u32_e32 v155, 0x40004, v155
	v_and_b32_e32 v154, 0xfff8fff8, v154
	v_and_b32_e32 v155, 0xfff8fff8, v155
	v_add_u32_e32 v194, 48, v32
	v_mad_i64_i32 v[194:195], vcc, v194, s29, v[192:193]
	global_store_dwordx4 v[194:195], v[152:155], off
	v_mfma_f32_32x32x16_f16 v[68:83], v[128:131], v[128:131], 0
	v_lshlrev_b32_e32 v183, 2, v181
	v_readlane_b32 s12, v251, 60
	v_readlane_b32 s13, v251, 59
	s_nop 1
	v_add_u32_e32 v189, s12, v183
	v_add_u32_e32 v183, s13, v183
	ds_read_b128 v[176:179], v189
	ds_read_b128 v[140:143], v189 offset:16
	s_cmp_eq_u32 s48, 0
	s_cbranch_scc0 .Lffn_no_ed
	ds_read_b128 v[136:139], v183 offset:1024
	ds_read_b128 v[144:147], v183 offset:1040
	s_branch .Lffn_ed_done

;     __device__ __forceinline__ void operator()(const f32x4 (&acc)[2][2][4][2], const GUnit& u, int wr, int wc, int fr, int fq, LAS unsigned char* lds) const {
;     ...
; #pragma unroll
;                         for (int q = 0; q < 2; ++q) gp[m][2 * n + q] = pk_f16(acc[ai][1][m][n][2 * q], acc[ai][1][m][n][2 * q + 1]);
; #pragma unroll
;                 for (int n = 0; n < 2; ++n) {
;                     const f32x4 eu = c > 0 ? *(const LAS f32x4*)(EL + ((c - 1) * 2 + 1) * 128 + wc * 32 + 8 * fqL + 4 * n) : (f32x4){0.f, 0.f, 0.f, 0.f};
;                     const f32x4 ed = c < 3 ? *(const LAS f32x4*)(EL + ((c + 1) * 2 + 0) * 128 + wc * 32 + 8 * fqL + 4 * n) : (f32x4){0.f, 0.f, 0.f, 0.f};
; #pragma unroll
;                     for (int q = 0; q < 2; ++q) { eup[2 * n + q] = pk_f16(eu[2 * q], eu[2 * q + 1]); edp[2 * n + q] = pk_f16(ed[2 * q], ed[2 * q + 1]); } }
; #pragma unroll
;                 for (int m = 0; m < 4; ++m) {
;                     u32x4 UP, DN, GG;
; #pragma unroll
;                     for (int j = 0; j < 4; ++j) { const int g = (int)gp[m][j];
;                         const int oldu = m > 0 ? shl_((int)gp[m > 0 ? m - 1 : 0][j], lane15) : (int)eup[j];
;                         const int ups = __builtin_amdgcn_update_dpp(0, g, 0x111, 0xf, 0xf, true);
;                         const int oldd = m < 3 ? shl_((int)gp[m < 3 ? m + 1 : 3][j], lane0r) : (int)edp[j];
;                         const int dns = __builtin_amdgcn_update_dpp(0, g, 0x101, 0xf, 0xf, true);
;                         UP[j] = (unsigned)(frL == 0 ? oldu : ups); DN[j] = (unsigned)(frL == 15 ? oldd : dns); GG[j] = (unsigned)g; }
;                     const f16x8 uph = __builtin_bit_cast(f16x8, UP), dnh = __builtin_bit_cast(f16x8, DN), ggh = __builtin_bit_cast(f16x8, GG);
;                     f16x2 yv[4];
;                     yv[0] = __builtin_shufflevector(uph, uph, 0, 1) * w0p[0] + __builtin_shufflevector(ggh, ggh, 0, 1) * w1p[0] + __builtin_shufflevector(dnh, dnh, 0, 1) * w2p[0] + bbp[0];
;                     yv[1] = __builtin_shufflevector(uph, uph, 2, 3) * w0p[1] + __builtin_shufflevector(ggh, ggh, 2, 3) * w1p[1] + __builtin_shufflevector(dnh, dnh, 2, 3) * w2p[1] + bbp[1];
;                     yv[2] = __builtin_shufflevector(uph, uph, 4, 5) * w0p[2] + __builtin_shufflevector(ggh, ggh, 4, 5) * w1p[2] + __builtin_shufflevector(dnh, dnh, 4, 5) * w2p[2] + bbp[2];
.Lffn_ed_done:
	s_waitcnt lgkmcnt(0)
	v_cvt_pk_f16_f32 v172, v176, v177
	v_cvt_pk_f16_f32 v173, v178, v179
	v_cvt_pk_f16_f32 v174, v140, v141
	v_cvt_pk_f16_f32 v175, v142, v143
	v_cvt_pk_f16_f32 v132, v136, v137
	v_cvt_pk_f16_f32 v133, v138, v139
	v_cvt_pk_f16_f32 v134, v144, v145
	v_cvt_pk_f16_f32 v135, v146, v147
	v_cvt_pk_f16_f32 v140, v56, v57
	v_cvt_pk_f16_f32 v141, v58, v59
	v_cvt_pk_f16_f32 v142, v52, v53
	v_cvt_pk_f16_f32 v143, v54, v55
	v_cvt_pk_f16_f32 v144, v40, v41
	v_cvt_pk_f16_f32 v145, v42, v43
	v_cvt_pk_f16_f32 v146, v36, v37
	v_cvt_pk_f16_f32 v147, v38, v39
	v_mov_b32_dpp v172, v140 row_shr:1 row_mask:0xf bank_mask:0xf
	v_mov_b32_dpp v173, v141 row_shr:1 row_mask:0xf bank_mask:0xf
	v_mov_b32_dpp v137, v144 row_ror:15 row_mask:0xf bank_mask:0xf
	v_mov_b32_dpp v177, v145 row_ror:15 row_mask:0xf bank_mask:0xf
	v_mov_b32_dpp v137, v140 row_shl:1 row_mask:0xf bank_mask:0xf
	v_mov_b32_dpp v177, v141 row_shl:1 row_mask:0xf bank_mask:0xf
	v_pk_fma_f16 v136, v172, v164, v160
	v_pk_fma_f16 v176, v173, v165, v161
	v_pk_fma_f16 v136, v140, v168, v136
	v_pk_fma_f16 v176, v141, v169, v176
	v_pk_fma_f16 v136, v137, v156, v136
	v_pk_fma_f16 v176, v177, v157, v176
	v_and_b32_e32 v137, 0x7fff7fff, v136
	v_and_b32_e32 v177, 0x7fff7fff, v176
	v_pk_fma_f16 v138, v137, s45, 1.0 op_sel_hi:[1,0,0]
	v_pk_fma_f16 v178, v177, s45, 1.0 op_sel_hi:[1,0,0]
	v_rcp_f16_e32 v139, v138
	v_rcp_f16_e32 v179, v178
	v_rcp_f16_sdwa v139, v138 dst_sel:WORD_1 dst_unused:UNUSED_PRESERVE src0_sel:WORD_1
	v_rcp_f16_sdwa v179, v178 dst_sel:WORD_1 dst_unused:UNUSED_PRESERVE src0_sel:WORD_1
	v_pk_fma_f16 v138, v139, s55, v228 op_sel_hi:[1,0,0]
	v_pk_fma_f16 v178, v179, s55, v228 op_sel_hi:[1,0,0]
	v_pk_fma_f16 v138, v139, v138, s65 op_sel_hi:[1,1,0]
	v_pk_fma_f16 v178, v179, v178, s65 op_sel_hi:[1,1,0]
	v_pk_fma_f16 v138, v139, v138, s68 op_sel_hi:[1,1,0]
	v_pk_fma_f16 v178, v179, v178, s68 op_sel_hi:[1,1,0]
	v_pk_fma_f16 v138, v139, v138, s69 op_sel_hi:[1,1,0]
	v_pk_fma_f16 v178, v179, v178, s69 op_sel_hi:[1,1,0]
	v_pk_mul_f16 v138, v139, v138
	v_pk_mul_f16 v178, v179, v178
	v_pk_mul_f16 v139, v136, v136
	v_pk_mul_f16 v179, v176, v176
	v_pk_mul_f16 v139, v139, s72 op_sel_hi:[1,0]
	v_pk_mul_f16 v179, v179, s72 op_sel_hi:[1,0]
	v_exp_f16_e32 v183, v139
	v_exp_f16_e32 v189, v179
	v_exp_f16_sdwa v183, v139 dst_sel:WORD_1 dst_unused:UNUSED_PRESERVE src0_sel:WORD_1
	v_exp_f16_sdwa v189, v179 dst_sel:WORD_1 dst_unused:UNUSED_PRESERVE src0_sel:WORD_1
	v_pk_mul_f16 v138, v183, v138
	v_pk_mul_f16 v178, v189, v178
	v_pk_max_f16 v136, v136, 0
	v_pk_max_f16 v176, v176, 0
	v_pk_fma_f16 v136, v137, v138, v136 neg_lo:[1,0,0] neg_hi:[1,0,0]
	v_pk_fma_f16 v176, v177, v178, v176 neg_lo:[1,0,0] neg_hi:[1,0,0]
	v_cvt_pk_f16_f32 v139, v64, v65
	v_cvt_pk_f16_f32 v179, v66, v67
	v_pk_mul_f16 v152, v139, v136
	v_pk_mul_f16 v153, v179, v176
	v_add_u32_e32 v152, 0x40004, v152
	v_add_u32_e32 v153, 0x40004, v153
	v_and_b32_e32 v152, 0xfff8fff8, v152
	v_and_b32_e32 v153, 0xfff8fff8, v153
	v_mov_b32_dpp v174, v142 row_shr:1 row_mask:0xf bank_mask:0xf
	v_mov_b32_dpp v175, v143 row_shr:1 row_mask:0xf bank_mask:0xf
	v_mov_b32_dpp v137, v146 row_ror:15 row_mask:0xf bank_mask:0xf
	v_mov_b32_dpp v177, v147 row_ror:15 row_mask:0xf bank_mask:0xf
	v_mov_b32_dpp v137, v142 row_shl:1 row_mask:0xf bank_mask:0xf
	v_mov_b32_dpp v177, v143 row_shl:1 row_mask:0xf bank_mask:0xf
	v_pk_fma_f16 v136, v174, v166, v162
	v_pk_fma_f16 v176, v175, v167, v163
	v_pk_fma_f16 v136, v142, v170, v136
	v_pk_fma_f16 v176, v143, v171, v176
	v_pk_fma_f16 v136, v137, v158, v136
	v_pk_fma_f16 v176, v177, v159, v176
	v_and_b32_e32 v137, 0x7fff7fff, v136
	v_and_b32_e32 v177, 0x7fff7fff, v176
	v_pk_fma_f16 v138, v137, s45, 1.0 op_sel_hi:[1,0,0]
	v_pk_fma_f16 v178, v177, s45, 1.0 op_sel_hi:[1,0,0]
	v_rcp_f16_e32 v139, v138
	v_rcp_f16_e32 v179, v178
	v_rcp_f16_sdwa v139, v138 dst_sel:WORD_1 dst_unused:UNUSED_PRESERVE src0_sel:WORD_1
	v_rcp_f16_sdwa v179, v178 dst_sel:WORD_1 dst_unused:UNUSED_PRESERVE src0_sel:WORD_1
	v_pk_fma_f16 v138, v139, s55, v228 op_sel_hi:[1,0,0]
	v_pk_fma_f16 v178, v179, s55, v228 op_sel_hi:[1,0,0]
	v_pk_fma_f16 v138, v139, v138, s65 op_sel_hi:[1,1,0]
	v_pk_fma_f16 v178, v179, v178, s65 op_sel_hi:[1,1,0]
	v_pk_fma_f16 v138, v139, v138, s68 op_sel_hi:[1,1,0]
	v_pk_fma_f16 v178, v179, v178, s68 op_sel_hi:[1,1,0]
	v_pk_fma_f16 v138, v139, v138, s69 op_sel_hi:[1,1,0]
	v_pk_fma_f16 v178, v179, v178, s69 op_sel_hi:[1,1,0]
	v_pk_mul_f16 v138, v139, v138
	v_pk_mul_f16 v178, v179, v178
	v_pk_mul_f16 v139, v136, v136
	v_pk_mul_f16 v179, v176, v176
	v_pk_mul_f16 v139, v139, s72 op_sel_hi:[1,0]
	v_pk_mul_f16 v179, v179, s72 op_sel_hi:[1,0]
	v_exp_f16_e32 v183, v139
	v_exp_f16_e32 v189, v179
	v_exp_f16_sdwa v183, v139 dst_sel:WORD_1 dst_unused:UNUSED_PRESERVE src0_sel:WORD_1
	v_exp_f16_sdwa v189, v179 dst_sel:WORD_1 dst_unused:UNUSED_PRESERVE src0_sel:WORD_1
	v_pk_mul_f16 v138, v183, v138
	v_pk_mul_f16 v178, v189, v178
	v_pk_max_f16 v136, v136, 0
	v_pk_max_f16 v176, v176, 0
	v_pk_fma_f16 v136, v137, v138, v136 neg_lo:[1,0,0] neg_hi:[1,0,0]
	v_pk_fma_f16 v176, v177, v178, v176 neg_lo:[1,0,0] neg_hi:[1,0,0]
	v_cvt_pk_f16_f32 v139, v60, v61
	v_cvt_pk_f16_f32 v179, v62, v63
	v_pk_mul_f16 v154, v139, v136
	v_pk_mul_f16 v155, v179, v176
	v_add_u32_e32 v154, 0x40004, v154
	v_add_u32_e32 v155, 0x40004, v155
	v_and_b32_e32 v154, 0xfff8fff8, v154
	v_and_b32_e32 v155, 0xfff8fff8, v155
	v_add_u32_e32 v194, 0x80, v32
	v_mad_i64_i32 v[194:195], vcc, v194, s29, v[192:193]
	global_store_dwordx4 v[194:195], v[152:155], off
	v_mfma_f32_32x32x16_f16 v[52:67], v[128:131], v[128:131], 0
	v_cvt_pk_f16_f32 v148, v20, v21
	v_cvt_pk_f16_f32 v149, v22, v23
; __device__ __forceinline__ int shl_(int v, int src_lane) { return __builtin_amdgcn_ds_bpermute(src_lane << 2, v); }
;     __device__ __forceinline__ void operator()(const f32x4 (&acc)[2][2][4][2], const GUnit& u, int wr, int wc, int fr, int fq, LAS unsigned char* lds) const {
;     ...
;                 for (int m = 0; m < 4; ++m) {
;                     u32x4 UP, DN, GG;
; #pragma unroll
;                     for (int j = 0; j < 4; ++j) { const int g = (int)gp[m][j];
;                         const int oldu = m > 0 ? shl_((int)gp[m > 0 ? m - 1 : 0][j], lane15) : (int)eup[j];
;                         const int ups = __builtin_amdgcn_update_dpp(0, g, 0x111, 0xf, 0xf, true);
;                         const int oldd = m < 3 ? shl_((int)gp[m < 3 ? m + 1 : 3][j], lane0r) : (int)edp[j];
;                         const int dns = __builtin_amdgcn_update_dpp(0, g, 0x101, 0xf, 0xf, true);
;                         UP[j] = (unsigned)(frL == 0 ? oldu : ups); DN[j] = (unsigned)(frL == 15 ? oldd : dns); GG[j] = (unsigned)g; }
;                     const f16x8 uph = __builtin_bit_cast(f16x8, UP), dnh = __builtin_bit_cast(f16x8, DN), ggh = __builtin_bit_cast(f16x8, GG);
;                     f16x2 yv[4];
;                     yv[0] = __builtin_shufflevector(uph, uph, 0, 1) * w0p[0] + __builtin_shufflevector(ggh, ggh, 0, 1) * w1p[0] + __builtin_shufflevector(dnh, dnh, 0, 1) * w2p[0] + bbp[0];
;                     yv[1] = __builtin_shufflevector(uph, uph, 2, 3) * w0p[1] + __builtin_shufflevector(ggh, ggh, 2, 3) * w1p[1] + __builtin_shufflevector(dnh, dnh, 2, 3) * w2p[1] + bbp[1];
;                     yv[2] = __builtin_shufflevector(uph, uph, 4, 5) * w0p[2] + __builtin_shufflevector(ggh, ggh, 4, 5) * w1p[2] + __builtin_shufflevector(dnh, dnh, 4, 5) * w2p[2] + bbp[2];
;                     yv[3] = __builtin_shufflevector(uph, uph, 6, 7) * w0p[3] + __builtin_shufflevector(ggh, ggh, 6, 7) * w1p[3] + __builtin_shufflevector(dnh, dnh, 6, 7) * w2p[3] + bbp[3];
;                     u32x4 o;
; #pragma unroll
;                     for (int n = 0; n < 2; ++n)
; #pragma unroll
;                         for (int q = 0; q < 2; ++q) { const int j = 2 * n + q;
	v_cvt_pk_f16_f32 v150, v16, v17
	v_cvt_pk_f16_f32 v151, v18, v19
	v_mov_b32_dpp v136, v140 row_ror:1 row_mask:0xf bank_mask:0xf
	v_mov_b32_dpp v176, v141 row_ror:1 row_mask:0xf bank_mask:0xf
	v_mov_b32_dpp v136, v144 row_shr:1 row_mask:0xf bank_mask:0xf
	v_mov_b32_dpp v176, v145 row_shr:1 row_mask:0xf bank_mask:0xf
	v_mov_b32_dpp v137, v148 row_ror:15 row_mask:0xf bank_mask:0xf
	v_mov_b32_dpp v177, v149 row_ror:15 row_mask:0xf bank_mask:0xf
	v_mov_b32_dpp v137, v144 row_shl:1 row_mask:0xf bank_mask:0xf
	v_mov_b32_dpp v177, v145 row_shl:1 row_mask:0xf bank_mask:0xf
	v_pk_fma_f16 v136, v136, v164, v160
	v_pk_fma_f16 v176, v176, v165, v161
	v_pk_fma_f16 v136, v144, v168, v136
	v_pk_fma_f16 v176, v145, v169, v176
	v_pk_fma_f16 v136, v137, v156, v136
	v_pk_fma_f16 v176, v177, v157, v176
	v_and_b32_e32 v137, 0x7fff7fff, v136
	v_and_b32_e32 v177, 0x7fff7fff, v176
	v_pk_fma_f16 v138, v137, s45, 1.0 op_sel_hi:[1,0,0]
	v_pk_fma_f16 v178, v177, s45, 1.0 op_sel_hi:[1,0,0]
	v_rcp_f16_e32 v139, v138
	v_rcp_f16_e32 v179, v178
	v_rcp_f16_sdwa v139, v138 dst_sel:WORD_1 dst_unused:UNUSED_PRESERVE src0_sel:WORD_1
	v_rcp_f16_sdwa v179, v178 dst_sel:WORD_1 dst_unused:UNUSED_PRESERVE src0_sel:WORD_1
	v_pk_fma_f16 v138, v139, s55, v228 op_sel_hi:[1,0,0]
	v_pk_fma_f16 v178, v179, s55, v228 op_sel_hi:[1,0,0]
	v_pk_fma_f16 v138, v139, v138, s65 op_sel_hi:[1,1,0]
	v_pk_fma_f16 v178, v179, v178, s65 op_sel_hi:[1,1,0]
	v_pk_fma_f16 v138, v139, v138, s68 op_sel_hi:[1,1,0]
	v_pk_fma_f16 v178, v179, v178, s68 op_sel_hi:[1,1,0]
	v_pk_fma_f16 v138, v139, v138, s69 op_sel_hi:[1,1,0]
	v_pk_fma_f16 v178, v179, v178, s69 op_sel_hi:[1,1,0]
	v_pk_mul_f16 v138, v139, v138
	v_pk_mul_f16 v178, v179, v178
	v_pk_mul_f16 v139, v136, v136
	v_pk_mul_f16 v179, v176, v176
	v_pk_mul_f16 v139, v139, s72 op_sel_hi:[1,0]
	v_pk_mul_f16 v179, v179, s72 op_sel_hi:[1,0]
	v_exp_f16_e32 v183, v139
	v_exp_f16_e32 v189, v179
	v_exp_f16_sdwa v183, v139 dst_sel:WORD_1 dst_unused:UNUSED_PRESERVE src0_sel:WORD_1
	v_exp_f16_sdwa v189, v179 dst_sel:WORD_1 dst_unused:UNUSED_PRESERVE src0_sel:WORD_1
	v_pk_mul_f16 v138, v183, v138
	v_pk_mul_f16 v178, v189, v178
	v_pk_max_f16 v136, v136, 0
	v_pk_max_f16 v176, v176, 0
	v_pk_fma_f16 v136, v137, v138, v136 neg_lo:[1,0,0] neg_hi:[1,0,0]
	v_pk_fma_f16 v176, v177, v178, v176 neg_lo:[1,0,0] neg_hi:[1,0,0]
	v_cvt_pk_f16_f32 v139, v48, v49
	v_cvt_pk_f16_f32 v179, v50, v51
	v_pk_mul_f16 v152, v139, v136
	v_pk_mul_f16 v153, v179, v176
	v_add_u32_e32 v152, 0x40004, v152
	v_add_u32_e32 v153, 0x40004, v153
	v_and_b32_e32 v152, 0xfff8fff8, v152
	v_and_b32_e32 v153, 0xfff8fff8, v153
	v_mov_b32_dpp v136, v142 row_ror:1 row_mask:0xf bank_mask:0xf
	v_mov_b32_dpp v176, v143 row_ror:1 row_mask:0xf bank_mask:0xf
	v_mov_b32_dpp v136, v146 row_shr:1 row_mask:0xf bank_mask:0xf
	v_mov_b32_dpp v176, v147 row_shr:1 row_mask:0xf bank_mask:0xf
	v_mov_b32_dpp v137, v150 row_ror:15 row_mask:0xf bank_mask:0xf
	v_mov_b32_dpp v177, v151 row_ror:15 row_mask:0xf bank_mask:0xf
	v_mov_b32_dpp v137, v146 row_shl:1 row_mask:0xf bank_mask:0xf
	v_mov_b32_dpp v177, v147 row_shl:1 row_mask:0xf bank_mask:0xf
	v_pk_fma_f16 v136, v136, v166, v162
	v_pk_fma_f16 v176, v176, v167, v163
	v_pk_fma_f16 v136, v146, v170, v136
	v_pk_fma_f16 v176, v147, v171, v176
	v_pk_fma_f16 v136, v137, v158, v136
	v_pk_fma_f16 v176, v177, v159, v176
	v_and_b32_e32 v137, 0x7fff7fff, v136
	v_and_b32_e32 v177, 0x7fff7fff, v176
	v_pk_fma_f16 v138, v137, s45, 1.0 op_sel_hi:[1,0,0]
	v_pk_fma_f16 v178, v177, s45, 1.0 op_sel_hi:[1,0,0]
	v_rcp_f16_e32 v139, v138
	v_rcp_f16_e32 v179, v178
	v_rcp_f16_sdwa v139, v138 dst_sel:WORD_1 dst_unused:UNUSED_PRESERVE src0_sel:WORD_1
	v_rcp_f16_sdwa v179, v178 dst_sel:WORD_1 dst_unused:UNUSED_PRESERVE src0_sel:WORD_1
	v_pk_fma_f16 v138, v139, s55, v228 op_sel_hi:[1,0,0]
	v_pk_fma_f16 v178, v179, s55, v228 op_sel_hi:[1,0,0]
	v_pk_fma_f16 v138, v139, v138, s65 op_sel_hi:[1,1,0]
	v_pk_fma_f16 v178, v179, v178, s65 op_sel_hi:[1,1,0]
	v_pk_fma_f16 v138, v139, v138, s68 op_sel_hi:[1,1,0]
	v_pk_fma_f16 v178, v179, v178, s68 op_sel_hi:[1,1,0]
	v_pk_fma_f16 v138, v139, v138, s69 op_sel_hi:[1,1,0]
	v_pk_fma_f16 v178, v179, v178, s69 op_sel_hi:[1,1,0]
	v_pk_mul_f16 v138, v139, v138
	v_pk_mul_f16 v178, v179, v178
	v_pk_mul_f16 v139, v136, v136
	v_pk_mul_f16 v179, v176, v176
	v_pk_mul_f16 v139, v139, s72 op_sel_hi:[1,0]
	v_pk_mul_f16 v179, v179, s72 op_sel_hi:[1,0]
	v_exp_f16_e32 v183, v139
	v_exp_f16_e32 v189, v179
	v_exp_f16_sdwa v183, v139 dst_sel:WORD_1 dst_unused:UNUSED_PRESERVE src0_sel:WORD_1
	v_exp_f16_sdwa v189, v179 dst_sel:WORD_1 dst_unused:UNUSED_PRESERVE src0_sel:WORD_1
	v_pk_mul_f16 v138, v183, v138
	v_pk_mul_f16 v178, v189, v178
	v_pk_max_f16 v136, v136, 0
	v_pk_max_f16 v176, v176, 0
	v_pk_fma_f16 v136, v137, v138, v136 neg_lo:[1,0,0] neg_hi:[1,0,0]
	v_pk_fma_f16 v176, v177, v178, v176 neg_lo:[1,0,0] neg_hi:[1,0,0]
	v_cvt_pk_f16_f32 v139, v44, v45
	v_cvt_pk_f16_f32 v179, v46, v47
	v_pk_mul_f16 v154, v139, v136
	v_pk_mul_f16 v155, v179, v176
	v_add_u32_e32 v154, 0x40004, v154
	v_add_u32_e32 v155, 0x40004, v155
	v_and_b32_e32 v154, 0xfff8fff8, v154
	v_and_b32_e32 v155, 0xfff8fff8, v155
	v_add_u32_e32 v194, 0x90, v32
	v_mad_i64_i32 v[194:195], vcc, v194, s29, v[192:193]
	global_store_dwordx4 v[194:195], v[152:155], off
	v_mfma_f32_32x32x16_f16 v[36:51], v[128:131], v[128:131], 0
	v_cvt_pk_f16_f32 v140, v4, v5
	v_cvt_pk_f16_f32 v141, v6, v7
	v_cvt_pk_f16_f32 v142, v0, v1
	v_cvt_pk_f16_f32 v143, v2, v3
	v_mov_b32_dpp v136, v144 row_ror:1 row_mask:0xf bank_mask:0xf
	v_mov_b32_dpp v176, v145 row_ror:1 row_mask:0xf bank_mask:0xf
	v_mov_b32_dpp v136, v148 row_shr:1 row_mask:0xf bank_mask:0xf
; __device__ __forceinline__ int shl_(int v, int src_lane) { return __builtin_amdgcn_ds_bpermute(src_lane << 2, v); }
;     __device__ __forceinline__ void operator()(const f32x4 (&acc)[2][2][4][2], const GUnit& u, int wr, int wc, int fr, int fq, LAS unsigned char* lds) const {
;     ...
;                 for (int m = 0; m < 4; ++m) {
;                     u32x4 UP, DN, GG;
; #pragma unroll
;                     for (int j = 0; j < 4; ++j) { const int g = (int)gp[m][j];
;                         const int oldu = m > 0 ? shl_((int)gp[m > 0 ? m - 1 : 0][j], lane15) : (int)eup[j];
;                         const int ups = __builtin_amdgcn_update_dpp(0, g, 0x111, 0xf, 0xf, true);
;                         const int oldd = m < 3 ? shl_((int)gp[m < 3 ? m + 1 : 3][j], lane0r) : (int)edp[j];
;                         const int dns = __builtin_amdgcn_update_dpp(0, g, 0x101, 0xf, 0xf, true);
;                         UP[j] = (unsigned)(frL == 0 ? oldu : ups); DN[j] = (unsigned)(frL == 15 ? oldd : dns); GG[j] = (unsigned)g; }
;                     const f16x8 uph = __builtin_bit_cast(f16x8, UP), dnh = __builtin_bit_cast(f16x8, DN), ggh = __builtin_bit_cast(f16x8, GG);
;                     f16x2 yv[4];
;                     yv[0] = __builtin_shufflevector(uph, uph, 0, 1) * w0p[0] + __builtin_shufflevector(ggh, ggh, 0, 1) * w1p[0] + __builtin_shufflevector(dnh, dnh, 0, 1) * w2p[0] + bbp[0];
;                     yv[1] = __builtin_shufflevector(uph, uph, 2, 3) * w0p[1] + __builtin_shufflevector(ggh, ggh, 2, 3) * w1p[1] + __builtin_shufflevector(dnh, dnh, 2, 3) * w2p[1] + bbp[1];
;                     yv[2] = __builtin_shufflevector(uph, uph, 4, 5) * w0p[2] + __builtin_shufflevector(ggh, ggh, 4, 5) * w1p[2] + __builtin_shufflevector(dnh, dnh, 4, 5) * w2p[2] + bbp[2];
;                     yv[3] = __builtin_shufflevector(uph, uph, 6, 7) * w0p[3] + __builtin_shufflevector(ggh, ggh, 6, 7) * w1p[3] + __builtin_shufflevector(dnh, dnh, 6, 7) * w2p[3] + bbp[3];
;                     u32x4 o;
; #pragma unroll
;                     for (int n = 0; n < 2; ++n)
; #pragma unroll
;                         for (int q = 0; q < 2; ++q) { const int j = 2 * n + q;
	v_mov_b32_dpp v176, v149 row_shr:1 row_mask:0xf bank_mask:0xf
	v_mov_b32_dpp v137, v140 row_ror:15 row_mask:0xf bank_mask:0xf
	v_mov_b32_dpp v177, v141 row_ror:15 row_mask:0xf bank_mask:0xf
	v_mov_b32_dpp v137, v148 row_shl:1 row_mask:0xf bank_mask:0xf
	v_mov_b32_dpp v177, v149 row_shl:1 row_mask:0xf bank_mask:0xf
	v_pk_fma_f16 v136, v136, v164, v160
	v_pk_fma_f16 v176, v176, v165, v161
	v_pk_fma_f16 v136, v148, v168, v136
	v_pk_fma_f16 v176, v149, v169, v176
	v_pk_fma_f16 v136, v137, v156, v136
	v_pk_fma_f16 v176, v177, v157, v176
	v_and_b32_e32 v137, 0x7fff7fff, v136
	v_and_b32_e32 v177, 0x7fff7fff, v176
	v_pk_fma_f16 v138, v137, s45, 1.0 op_sel_hi:[1,0,0]
	v_pk_fma_f16 v178, v177, s45, 1.0 op_sel_hi:[1,0,0]
	v_rcp_f16_e32 v139, v138
	v_rcp_f16_e32 v179, v178
	v_rcp_f16_sdwa v139, v138 dst_sel:WORD_1 dst_unused:UNUSED_PRESERVE src0_sel:WORD_1
	v_rcp_f16_sdwa v179, v178 dst_sel:WORD_1 dst_unused:UNUSED_PRESERVE src0_sel:WORD_1
	v_pk_fma_f16 v138, v139, s55, v228 op_sel_hi:[1,0,0]
	v_pk_fma_f16 v178, v179, s55, v228 op_sel_hi:[1,0,0]
	v_pk_fma_f16 v138, v139, v138, s65 op_sel_hi:[1,1,0]
	v_pk_fma_f16 v178, v179, v178, s65 op_sel_hi:[1,1,0]
	v_pk_fma_f16 v138, v139, v138, s68 op_sel_hi:[1,1,0]
	v_pk_fma_f16 v178, v179, v178, s68 op_sel_hi:[1,1,0]
	v_pk_fma_f16 v138, v139, v138, s69 op_sel_hi:[1,1,0]
	v_pk_fma_f16 v178, v179, v178, s69 op_sel_hi:[1,1,0]
	v_pk_mul_f16 v138, v139, v138
	v_pk_mul_f16 v178, v179, v178
	v_pk_mul_f16 v139, v136, v136
	v_pk_mul_f16 v179, v176, v176
	v_pk_mul_f16 v139, v139, s72 op_sel_hi:[1,0]
	v_pk_mul_f16 v179, v179, s72 op_sel_hi:[1,0]
	v_exp_f16_e32 v183, v139
	v_exp_f16_e32 v189, v179
	v_exp_f16_sdwa v183, v139 dst_sel:WORD_1 dst_unused:UNUSED_PRESERVE src0_sel:WORD_1
	v_exp_f16_sdwa v189, v179 dst_sel:WORD_1 dst_unused:UNUSED_PRESERVE src0_sel:WORD_1
	v_pk_mul_f16 v138, v183, v138
	v_pk_mul_f16 v178, v189, v178
	v_pk_max_f16 v136, v136, 0
	v_pk_max_f16 v176, v176, 0
	v_pk_fma_f16 v136, v137, v138, v136 neg_lo:[1,0,0] neg_hi:[1,0,0]
	v_pk_fma_f16 v176, v177, v178, v176 neg_lo:[1,0,0] neg_hi:[1,0,0]
	v_cvt_pk_f16_f32 v139, v28, v29
	v_cvt_pk_f16_f32 v179, v30, v31
	v_pk_mul_f16 v152, v139, v136
	v_pk_mul_f16 v153, v179, v176
	v_add_u32_e32 v152, 0x40004, v152
	v_add_u32_e32 v153, 0x40004, v153
	v_and_b32_e32 v152, 0xfff8fff8, v152
	v_and_b32_e32 v153, 0xfff8fff8, v153
	v_mov_b32_dpp v136, v146 row_ror:1 row_mask:0xf bank_mask:0xf
	v_mov_b32_dpp v176, v147 row_ror:1 row_mask:0xf bank_mask:0xf
	v_mov_b32_dpp v136, v150 row_shr:1 row_mask:0xf bank_mask:0xf
	v_mov_b32_dpp v176, v151 row_shr:1 row_mask:0xf bank_mask:0xf
	v_mov_b32_dpp v137, v142 row_ror:15 row_mask:0xf bank_mask:0xf
	v_mov_b32_dpp v177, v143 row_ror:15 row_mask:0xf bank_mask:0xf
	v_mov_b32_dpp v137, v150 row_shl:1 row_mask:0xf bank_mask:0xf
	v_mov_b32_dpp v177, v151 row_shl:1 row_mask:0xf bank_mask:0xf
	v_pk_fma_f16 v136, v136, v166, v162
	v_pk_fma_f16 v176, v176, v167, v163
	v_pk_fma_f16 v136, v150, v170, v136
	v_pk_fma_f16 v176, v151, v171, v176
	v_pk_fma_f16 v136, v137, v158, v136
	v_pk_fma_f16 v176, v177, v159, v176
	v_and_b32_e32 v137, 0x7fff7fff, v136
	v_and_b32_e32 v177, 0x7fff7fff, v176
	v_pk_fma_f16 v138, v137, s45, 1.0 op_sel_hi:[1,0,0]
	v_pk_fma_f16 v178, v177, s45, 1.0 op_sel_hi:[1,0,0]
	v_rcp_f16_e32 v139, v138
	v_rcp_f16_e32 v179, v178
	v_rcp_f16_sdwa v139, v138 dst_sel:WORD_1 dst_unused:UNUSED_PRESERVE src0_sel:WORD_1
	v_rcp_f16_sdwa v179, v178 dst_sel:WORD_1 dst_unused:UNUSED_PRESERVE src0_sel:WORD_1
	v_pk_fma_f16 v138, v139, s55, v228 op_sel_hi:[1,0,0]
	v_pk_fma_f16 v178, v179, s55, v228 op_sel_hi:[1,0,0]
	v_pk_fma_f16 v138, v139, v138, s65 op_sel_hi:[1,1,0]
	v_pk_fma_f16 v178, v179, v178, s65 op_sel_hi:[1,1,0]
	v_pk_fma_f16 v138, v139, v138, s68 op_sel_hi:[1,1,0]
	v_pk_fma_f16 v178, v179, v178, s68 op_sel_hi:[1,1,0]
	v_pk_fma_f16 v138, v139, v138, s69 op_sel_hi:[1,1,0]
	v_pk_fma_f16 v178, v179, v178, s69 op_sel_hi:[1,1,0]
	v_pk_mul_f16 v138, v139, v138
	v_pk_mul_f16 v178, v179, v178
	v_pk_mul_f16 v139, v136, v136
	v_pk_mul_f16 v179, v176, v176
	v_pk_mul_f16 v139, v139, s72 op_sel_hi:[1,0]
	v_pk_mul_f16 v179, v179, s72 op_sel_hi:[1,0]
	v_exp_f16_e32 v183, v139
	v_exp_f16_e32 v189, v179
	v_exp_f16_sdwa v183, v139 dst_sel:WORD_1 dst_unused:UNUSED_PRESERVE src0_sel:WORD_1
	v_exp_f16_sdwa v189, v179 dst_sel:WORD_1 dst_unused:UNUSED_PRESERVE src0_sel:WORD_1
	v_pk_mul_f16 v138, v183, v138
	v_pk_mul_f16 v178, v189, v178
	v_pk_max_f16 v136, v136, 0
	v_pk_max_f16 v176, v176, 0
	v_pk_fma_f16 v136, v137, v138, v136 neg_lo:[1,0,0] neg_hi:[1,0,0]
	v_pk_fma_f16 v176, v177, v178, v176 neg_lo:[1,0,0] neg_hi:[1,0,0]
	v_cvt_pk_f16_f32 v139, v24, v25
	v_cvt_pk_f16_f32 v179, v26, v27
	v_pk_mul_f16 v154, v139, v136
	v_pk_mul_f16 v155, v179, v176
	v_add_u32_e32 v154, 0x40004, v154
	v_add_u32_e32 v155, 0x40004, v155
	v_and_b32_e32 v154, 0xfff8fff8, v154
	v_and_b32_e32 v155, 0xfff8fff8, v155
	v_add_u32_e32 v194, 0xa0, v32
	v_mad_i64_i32 v[194:195], vcc, v194, s29, v[192:193]
	global_store_dwordx4 v[194:195], v[152:155], off
	v_mfma_f32_32x32x16_f16 v[16:31], v[128:131], v[128:131], 0
	v_mov_b32_dpp v136, v148 row_ror:1 row_mask:0xf bank_mask:0xf
	v_mov_b32_dpp v176, v150 row_ror:1 row_mask:0xf bank_mask:0xf
	v_mov_b32_dpp v136, v140 row_shr:1 row_mask:0xf bank_mask:0xf
	v_mov_b32_dpp v176, v142 row_shr:1 row_mask:0xf bank_mask:0xf
	v_mov_b32_dpp v132, v140 row_shl:1 row_mask:0xf bank_mask:0xf
	v_mov_b32_dpp v134, v142 row_shl:1 row_mask:0xf bank_mask:0xf
	v_pk_fma_f16 v136, v136, v164, v160
	v_pk_fma_f16 v176, v176, v166, v162
	v_pk_fma_f16 v136, v140, v168, v136
	v_pk_fma_f16 v176, v142, v170, v176
	v_pk_fma_f16 v136, v132, v156, v136
	v_pk_fma_f16 v176, v134, v158, v176
	v_mov_b32_dpp v137, v149 row_ror:1 row_mask:0xf bank_mask:0xf
	v_mov_b32_dpp v177, v151 row_ror:1 row_mask:0xf bank_mask:0xf
	v_mov_b32_dpp v137, v141 row_shr:1 row_mask:0xf bank_mask:0xf
	v_mov_b32_dpp v177, v143 row_shr:1 row_mask:0xf bank_mask:0xf
	v_mov_b32_dpp v133, v141 row_shl:1 row_mask:0xf bank_mask:0xf
	v_mov_b32_dpp v135, v143 row_shl:1 row_mask:0xf bank_mask:0xf
	v_pk_fma_f16 v137, v137, v165, v161
	v_pk_fma_f16 v177, v177, v167, v163
	v_pk_fma_f16 v137, v141, v169, v137
	v_pk_fma_f16 v177, v143, v171, v177
	v_pk_fma_f16 v137, v133, v157, v137
	v_pk_fma_f16 v177, v135, v159, v177
	s_cmp_lg_u32 s48, 0
	s_cbranch_scc0 .Lffn_side_bot_skip
;     __device__ __forceinline__ void operator()(const f32x4 (&acc)[2][2][4][2], const GUnit& u, int wr, int wc, int fr, int fq, LAS unsigned char* lds) const {
;     ...
;                             if (m == 0 && c == 0 && frL == 0 && pmod != 0) { const size_t off = (size_t)(u.pm * 2 + 0) * DFF + fb + 4 * n + 2 * q; *(f32x2*)(GB + off) = (f32x2){acc[ai][1][0][n][2 * q], acc[ai][1][0][n][2 * q + 1]}; *(f32x2*)(YP + off) = (f32x2){(float)yv[j][0], (float)yv[j][1]}; *(f32x2*)(VB + off) = (f32x2){acc[ai][0][0][n][2 * q], acc[ai][0][0][n][2 * q + 1]}; }
;                             if (m == 3 && c == 3 && frL == 15 && pmod != 7) { const size_t off = (size_t)(u.pm * 2 + 1) * DFF + fb + 4 * n + 2 * q; *(f32x2*)(GB + off) = (f32x2){acc[ai][1][3][n][2 * q], acc[ai][1][3][n][2 * q + 1]}; *(f32x2*)(YP + off) = (f32x2){(float)yv[j][0], (float)yv[j][1]}; *(f32x2*)(VB + off) = (f32x2){acc[ai][0][3][n][2 * q], acc[ai][0][3][n][2 * q + 1]}; }
;                             const f16x2 vp = {(f16)acc[ai][0][m][n][2 * q], (f16)acc[ai][0][m][n][2 * q + 1]};
;                             o[j] = rd<D_A2>(__builtin_bit_cast(unsigned, gelu_h2(yv[j]) * vp)); }
;                     *(u32x4*)(A2 + (size_t)(growL + ai * 128 + m * 16) * DFF + fb) = o;
	s_cmp_lg_u32 s36, 7
	s_cbranch_scc0 .Lffn_side_bot_skip
	s_and_saveexec_b64 s[80:81], s[8:9]
	s_lshl_b32 s12, s37, 1
	s_add_i32 s12, s12, 1
	v_mov_b32_e32 v152, 0xb00
	v_mad_i64_i32 v[152:153], vcc, s12, v152, v[190:191]
	v_readlane_b32 s12, v251, 22
	v_readlane_b32 s13, v251, 23
	v_lshlrev_b64 v[152:153], 2, v[152:153]
	s_nop 1
	v_lshl_add_u64 v[154:155], s[12:13], 0, v[152:153]
	global_store_dwordx2 v[154:155], v[4:5], off
	global_store_dwordx2 v[154:155], v[6:7], off offset:8
	global_store_dwordx2 v[154:155], v[0:1], off offset:16
	global_store_dwordx2 v[154:155], v[2:3], off offset:24
	v_readlane_b32 s12, v251, 24
	v_readlane_b32 s13, v251, 25
	v_cvt_f32_f16_e32 v138, v136
	v_cvt_f32_f16_sdwa v139, v136 dst_sel:DWORD dst_unused:UNUSED_PAD src0_sel:WORD_1
	v_lshl_add_u64 v[154:155], s[12:13], 0, v[152:153]
	global_store_dwordx2 v[154:155], v[138:139], off
	v_cvt_f32_f16_e32 v178, v137
	v_cvt_f32_f16_sdwa v179, v137 dst_sel:DWORD dst_unused:UNUSED_PAD src0_sel:WORD_1
	s_nop 0
	global_store_dwordx2 v[154:155], v[178:179], off offset:8
	v_cvt_f32_f16_e32 v138, v176
	v_cvt_f32_f16_sdwa v139, v176 dst_sel:DWORD dst_unused:UNUSED_PAD src0_sel:WORD_1
	s_nop 0
	global_store_dwordx2 v[154:155], v[138:139], off offset:16
	v_cvt_f32_f16_e32 v178, v177
	v_cvt_f32_f16_sdwa v179, v177 dst_sel:DWORD dst_unused:UNUSED_PAD src0_sel:WORD_1
	s_nop 0
	global_store_dwordx2 v[154:155], v[178:179], off offset:24
	v_readlane_b32 s12, v251, 26
	v_readlane_b32 s13, v251, 27
	s_nop 3
	v_lshl_add_u64 v[154:155], s[12:13], 0, v[152:153]
	global_store_dwordx2 v[154:155], v[12:13], off
	global_store_dwordx2 v[154:155], v[14:15], off offset:8
	global_store_dwordx2 v[154:155], v[8:9], off offset:16
	global_store_dwordx2 v[154:155], v[10:11], off offset:24
	s_or_b64 exec, exec, s[80:81]
.Lffn_side_bot_skip:
	v_and_b32_e32 v138, 0x7fff7fff, v136
	v_and_b32_e32 v178, 0x7fff7fff, v176
	v_pk_fma_f16 v139, v138, s45, 1.0 op_sel_hi:[1,0,0]
	v_pk_fma_f16 v179, v178, s45, 1.0 op_sel_hi:[1,0,0]
	v_rcp_f16_e32 v183, v139
	v_rcp_f16_e32 v189, v179
	v_rcp_f16_sdwa v183, v139 dst_sel:WORD_1 dst_unused:UNUSED_PRESERVE src0_sel:WORD_1
	v_rcp_f16_sdwa v189, v179 dst_sel:WORD_1 dst_unused:UNUSED_PRESERVE src0_sel:WORD_1
	v_pk_fma_f16 v139, v183, s55, v228 op_sel_hi:[1,0,0]
	v_pk_fma_f16 v179, v189, s55, v228 op_sel_hi:[1,0,0]
	v_pk_fma_f16 v139, v183, v139, s65 op_sel_hi:[1,1,0]
	v_pk_fma_f16 v179, v189, v179, s65 op_sel_hi:[1,1,0]
	v_pk_fma_f16 v139, v183, v139, s68 op_sel_hi:[1,1,0]
	v_pk_fma_f16 v179, v189, v179, s68 op_sel_hi:[1,1,0]
	v_pk_fma_f16 v139, v183, v139, s69 op_sel_hi:[1,1,0]
	v_pk_fma_f16 v179, v189, v179, s69 op_sel_hi:[1,1,0]
	v_pk_mul_f16 v139, v183, v139
	v_pk_mul_f16 v179, v189, v179
	v_pk_mul_f16 v183, v136, v136
	v_pk_mul_f16 v189, v176, v176
	v_pk_mul_f16 v183, v183, s72 op_sel_hi:[1,0]
	v_pk_mul_f16 v189, v189, s72 op_sel_hi:[1,0]
	v_exp_f16_e32 v153, v183
	v_exp_f16_e32 v155, v189
	v_exp_f16_sdwa v153, v183 dst_sel:WORD_1 dst_unused:UNUSED_PRESERVE src0_sel:WORD_1
	v_exp_f16_sdwa v155, v189 dst_sel:WORD_1 dst_unused:UNUSED_PRESERVE src0_sel:WORD_1
	v_pk_mul_f16 v139, v153, v139
	v_pk_mul_f16 v179, v155, v179
	v_pk_max_f16 v136, v136, 0
	v_pk_max_f16 v176, v176, 0
	v_pk_fma_f16 v136, v138, v139, v136 neg_lo:[1,0,0] neg_hi:[1,0,0]
	v_pk_fma_f16 v176, v178, v179, v176 neg_lo:[1,0,0] neg_hi:[1,0,0]
	v_cvt_pk_f16_f32 v183, v12, v13
	v_cvt_pk_f16_f32 v189, v8, v9
	v_pk_mul_f16 v152, v183, v136
	v_pk_mul_f16 v154, v189, v176
	v_add_u32_e32 v152, 0x40004, v152
	v_add_u32_e32 v154, 0x40004, v154
	v_and_b32_e32 v152, 0xfff8fff8, v152
	v_and_b32_e32 v154, 0xfff8fff8, v154
	v_and_b32_e32 v136, 0x7fff7fff, v137
	v_and_b32_e32 v176, 0x7fff7fff, v177
	v_pk_fma_f16 v138, v136, s45, 1.0 op_sel_hi:[1,0,0]
	v_pk_fma_f16 v178, v176, s45, 1.0 op_sel_hi:[1,0,0]
	v_rcp_f16_e32 v139, v138
	v_rcp_f16_e32 v179, v178
	v_rcp_f16_sdwa v139, v138 dst_sel:WORD_1 dst_unused:UNUSED_PRESERVE src0_sel:WORD_1
	v_rcp_f16_sdwa v179, v178 dst_sel:WORD_1 dst_unused:UNUSED_PRESERVE src0_sel:WORD_1
	v_pk_fma_f16 v138, v139, s55, v228 op_sel_hi:[1,0,0]
	v_pk_fma_f16 v178, v179, s55, v228 op_sel_hi:[1,0,0]
	v_pk_fma_f16 v138, v139, v138, s65 op_sel_hi:[1,1,0]
	v_pk_fma_f16 v178, v179, v178, s65 op_sel_hi:[1,1,0]
	v_pk_fma_f16 v138, v139, v138, s68 op_sel_hi:[1,1,0]
	v_pk_fma_f16 v178, v179, v178, s68 op_sel_hi:[1,1,0]
	v_pk_fma_f16 v138, v139, v138, s69 op_sel_hi:[1,1,0]
	v_pk_fma_f16 v178, v179, v178, s69 op_sel_hi:[1,1,0]
	v_pk_mul_f16 v138, v139, v138
	v_pk_mul_f16 v178, v179, v178
	v_pk_mul_f16 v139, v137, v137
	v_pk_mul_f16 v179, v177, v177
	v_pk_mul_f16 v139, v139, s72 op_sel_hi:[1,0]
	v_pk_mul_f16 v179, v179, s72 op_sel_hi:[1,0]
	v_exp_f16_e32 v183, v139
	v_exp_f16_e32 v189, v179
	v_exp_f16_sdwa v183, v139 dst_sel:WORD_1 dst_unused:UNUSED_PRESERVE src0_sel:WORD_1
	v_exp_f16_sdwa v189, v179 dst_sel:WORD_1 dst_unused:UNUSED_PRESERVE src0_sel:WORD_1
	v_pk_mul_f16 v138, v183, v138
	v_pk_mul_f16 v178, v189, v178
	v_pk_max_f16 v137, v137, 0
	v_pk_max_f16 v177, v177, 0
	v_pk_fma_f16 v137, v136, v138, v137 neg_lo:[1,0,0] neg_hi:[1,0,0]
	v_pk_fma_f16 v177, v176, v178, v177 neg_lo:[1,0,0] neg_hi:[1,0,0]
	v_cvt_pk_f16_f32 v139, v14, v15
	v_cvt_pk_f16_f32 v179, v10, v11
	v_pk_mul_f16 v153, v139, v137
	v_pk_mul_f16 v155, v179, v177
	v_add_u32_e32 v153, 0x40004, v153
	v_add_u32_e32 v155, 0x40004, v155
	v_and_b32_e32 v153, 0xfff8fff8, v153
	v_and_b32_e32 v155, 0xfff8fff8, v155
	v_add_u32_e32 v194, 0xb0, v32
	v_mad_i64_i32 v[194:195], vcc, v194, s29, v[192:193]
	global_store_dwordx4 v[194:195], v[152:155], off
	v_mfma_f32_32x32x16_f16 v[0:15], v[128:131], v[128:131], 0
